# mc_item<1> carried-state apply unrolled x4 with all state loads issued upfront (on top of mc_item<2> version)
# speedup vs baseline: 1.0067x; 1.0051x over previous
; #define LAS __attribute__((address_space(3)))
; #define BSYNC() do { asm volatile("s_waitcnt vmcnt(0) lgkmcnt(0)" ::: "memory"); __syncthreads(); } while (0)
; template <int TY> __device__ __forceinline__ void mc_item(const Params& p, ldsp lds, int item) {
;     ...
;     const int bh = item >> 5, c = item & 31, b = bh >> 2, h = bh & 3, sc = c / NB, jc = c % NB, row0 = b * 2048 + c * 64;
;     ...
;     if (TY != 2) lds += LDSSHIFT;
;     ...
;     ldsp QX = lds, QH2 = lds + o_qh, KTs = lds + o_kt, VTs = lds + o_vt, Pm = lds + o_pm; LAS float* RED = (LAS float*)(lds + o_red);
;     const bf16_t* Pb = (const bf16_t*)(p.ws + WS_P);
;     constexpr int PP = TY == 2 ? NO : NE;
;     const int ecol = TY ? 256 + h * 128 : h * 64;
;     if (TY == 2) stage_rows<DK>(QX, PQ, Pb + (size_t)row0 * NO + O_Q + h * 256, NO, tid);
;     else { stage_rows<DK>(QX, PQ, (const bf16_t*)(p.ws + WS_QT) + (size_t)row0 * 768 + ecol, 768, tid);
;            stage_rows<DK>(QH2, PQ, (const bf16_t*)(p.ws + WS_QH) + (size_t)row0 * 768 + ecol, 768, tid); }
;     f32x4 acc[ET][4];
; #pragma unroll
;     for (int ei = 0; ei < ET; ++ei)
; #pragma unroll
;         for (int tk = 0; tk < 4; ++tk) acc[ei][tk] = (f32x4){0.f, 0.f, 0.f, 0.f};
;     const int voff = TY == 0 ? E_VA + h * 128 : (TY == 1 ? E_IB + h * 128 : O_V + h * 512);
;     const int tt = wave & 3, sp = wave >> 2;
;     u32x4 kr[TY == 2 ? 4 : 1], vr[TY == 2 ? 8 : 1];
;     if constexpr (TY == 2) { const size_t rowq = (size_t)b * 2048 + (sc * NB) * 64;
;         ld_rows<256>(kr, Pb + rowq * NO + O_K + h * 256, NO, tid); ld_T<512>(vr, Pb + rowq * NO + voff, NO, wave, lane); }
;     for (int j = 0; j <= jc; ++j) { const size_t rowj = (size_t)b * 2048 + (sc * NB + j) * 64;
;         if constexpr (TY == 2) { st_rows<256>(KTs, PQ, kr, tid); st_T<512>(VTs, 72, vr, wave, lane); }
;         else { stage_rows<DK>(KTs, PQ, (const bf16_t*)(p.ws + WS_KT) + rowj * 768 + ecol, 768, tid);
;                stage_T<DV>(VTs, 72, Pb + rowj * PP + voff, PP, wave, lane); }
;         if constexpr (TY == 2) { __syncthreads(); if (j < jc) { const size_t rown = rowj + 64; ld_rows<256>(kr, Pb + rown * NO + O_K + h * 256, NO, tid); ld_T<512>(vr, Pb + rown * NO + voff, NO, wave, lane); } }
;         else BSYNC();
.LBB0_1243:
	s_lshl_b32 s1, s12, 11
	v_readlane_b32 s20, v254, 1
	s_or_b32 s17, s1, s20
	s_lshl_b32 s1, s8, 7
	v_mov_b32_e32 v22, v161
	s_and_b32 s1, s1, 0x180
	s_mul_i32 s13, s17, 0x600
	s_mul_hi_i32 s9, s17, 0x600
	s_add_u32 s18, s28, s13
	v_add_u32_e32 v6, 0x200, v22
	s_addc_u32 s19, s29, s9
	s_lshl_b32 s16, s1, 1
	v_ashrrev_i32_e32 v0, 31, v22
	v_ashrrev_i32_e32 v7, 31, v6
	s_add_u32 s18, s18, s16
	v_lshrrev_b32_e32 v0, 28, v0
	v_lshrrev_b32_e32 v7, 28, v7
	s_addc_u32 s19, s19, 0
	v_add_u32_e32 v0, v22, v0
	v_add_u32_e32 v7, v6, v7
	v_ashrrev_i32_e32 v23, 4, v0
	v_and_b32_e32 v0, 0x1ffffff0, v0
	v_mov_b64_e32 v[4:5], s[18:19]
	v_ashrrev_i32_e32 v42, 4, v7
	s_add_u32 s1, s22, s13
	v_sub_u32_e32 v2, v22, v0
	v_mad_i64_i32 v[0:1], s[18:19], v23, s60, v[4:5]
	v_mad_i64_i32 v[4:5], s[18:19], v42, s60, v[4:5]
	s_addc_u32 s9, s23, s9
	s_add_u32 s18, s1, s16
	s_addc_u32 s19, s9, 0
	v_mov_b64_e32 v[12:13], s[18:19]
	v_mad_i64_i32 v[8:9], s[18:19], v23, s60, v[12:13]
	v_mad_i64_i32 v[12:13], s[18:19], v42, s60, v[12:13]
	s_ashr_i32 s13, s12, 31
	s_lshl_b64 s[18:19], s[12:13], 11
	s_or_b32 s9, s18, s20
	s_mul_i32 s13, s19, 0x600
	s_mul_hi_u32 s18, s9, 0x600
	v_readfirstlane_b32 s0, v22
	s_add_i32 s20, s18, s13
	s_mul_i32 s13, s19, 0x1e00
	s_mul_hi_u32 s18, s9, 0x1e00
	s_ashr_i32 s1, s0, 6
	s_mul_i32 s21, s9, 0x600
	s_add_i32 s18, s18, s13
	s_mulk_i32 s9, 0x1e00
	v_and_b32_e32 v7, 0x1ffffff0, v7
	s_add_u32 s9, s26, s9
	v_sub_u32_e32 v6, v6, v7
	s_addc_u32 s13, s27, s18
	v_lshlrev_b32_e32 v40, 3, v6
	s_add_u32 s18, s9, s16
	v_ashrrev_i32_e32 v41, 31, v40
	s_addc_u32 s19, s13, 0
	s_lshl_b32 s9, s1, 5
	v_and_b32_e32 v16, 31, v22
	v_lshlrev_b64 v[24:25], 1, v[40:41]
	v_and_or_b32 v41, s9, 32, v16
	v_mul_u32_u24_e32 v16, 0xf00, v41
	v_lshlrev_b32_e32 v16, 1, v16
	v_lshl_add_u64 v[20:21], s[18:19], 0, v[16:17]
	v_bfe_u32 v16, v22, 5, 1
	v_lshlrev_b32_e32 v38, 3, v2
	v_and_or_b32 v16, s1, -2, v16
	s_lshl_b32 s13, s1, 4
	s_ashr_i32 s1, s0, 3
	v_ashrrev_i32_e32 v39, 31, v38
	s_andn2_b32 s1, s1, 31
	v_lshlrev_b64 v[18:19], 1, v[38:39]
	s_add_u32 s9, s72, s21
	v_lshl_add_u64 v[0:1], v[0:1], 0, v[18:19]
	s_addc_u32 s19, s73, s20
	global_load_dwordx4 v[0:3], v[0:1], off offset:512
	v_lshlrev_b32_e32 v26, 3, v16
	s_add_u32 s18, s9, s16
	v_lshl_add_u64 v[4:5], v[4:5], 0, v[24:25]
	v_ashrrev_i32_e32 v27, 31, v26
	s_addc_u32 s19, s19, 0
	global_load_dwordx4 v[4:7], v[4:5], off offset:512
	v_lshl_add_u64 v[8:9], v[8:9], 0, v[18:19]
	v_lshl_add_u64 v[34:35], v[26:27], 1, v[20:21]
	v_mov_b64_e32 v[26:27], s[18:19]
	global_load_dwordx4 v[8:11], v[8:9], off offset:512
	v_lshl_add_u64 v[12:13], v[12:13], 0, v[24:25]
	v_mad_i64_i32 v[20:21], s[18:19], v23, s60, v[26:27]
	v_mad_i64_i32 v[26:27], s[18:19], v42, s60, v[26:27]
	global_load_dwordx4 v[12:15], v[12:13], off offset:512
	v_lshl_add_u64 v[18:19], v[20:21], 0, v[18:19]
	v_lshl_add_u64 v[24:25], v[26:27], 0, v[24:25]
	global_load_dwordx4 v[18:21], v[18:19], off offset:512
	s_mov_b64 s[18:19], 0x1400
	global_load_dwordx4 v[26:29], v[24:25], off offset:512
	v_add_co_u32_e32 v24, vcc, s57, v34
	s_movk_i32 s20, 0x88
	s_nop 0
	v_addc_co_u32_e32 v25, vcc, 0, v35, vcc
	global_load_dwordx4 v[30:33], v[24:25], off offset:1024
	v_lshl_add_u64 v[24:25], v[34:35], 0, s[18:19]
	global_load_dwordx4 v[34:37], v[24:25], off offset:128
	v_mad_u64_u32 v[38:39], s[18:19], v23, s20, v[38:39]
	v_lshl_add_u32 v23, v38, 1, 0
	s_movk_i32 s9, 0x240
	v_and_b32_e32 v24, 15, v22
	v_and_b32_e32 v25, 48, v22
	s_waitcnt vmcnt(0)
	ds_write_b128 v23, v[0:3]
	v_mad_u64_u32 v[0:1], s[18:19], v42, s20, v[40:41]
	v_lshl_add_u32 v2, v0, 1, 0
	v_mul_lo_u32 v0, v16, s9
	ds_write_b128 v2, v[4:7]
	ds_write_b128 v23, v[8:11] offset:17408
	ds_write_b128 v2, v[12:15] offset:17408
	v_bfe_u32 v9, v22, 4, 2
	v_or_b32_e32 v0, v41, v0
	v_lshl_add_u32 v3, v0, 1, 0
	v_lshlrev_b32_e32 v8, 3, v9
	v_or_b32_e32 v0, s1, v24
	v_mad_u64_u32 v[0:1], s[18:19], v0, s20, v[8:9]
	ds_write_b128 v23, v[18:21] offset:34816
	ds_write_b128 v2, v[26:29] offset:34816
	ds_write_b16 v3, v30 offset:52224
	ds_write_b16_d16_hi v3, v30 offset:52368
	ds_write_b16 v3, v31 offset:52512
	ds_write_b16_d16_hi v3, v31 offset:52656
	ds_write_b16 v3, v32 offset:52800
	ds_write_b16_d16_hi v3, v32 offset:52944
	ds_write_b16 v3, v33 offset:53088
	ds_write_b16_d16_hi v3, v33 offset:53232
	ds_write_b16 v3, v34 offset:61440
	ds_write_b16_d16_hi v3, v34 offset:61584
	ds_write_b16 v3, v35 offset:61728
	ds_write_b16_d16_hi v3, v35 offset:61872
	ds_write_b16 v3, v36 offset:62016
	ds_write_b16_d16_hi v3, v36 offset:62160
	ds_write_b16 v3, v37 offset:62304
	ds_write_b16_d16_hi v3, v37 offset:62448
	v_lshl_add_u32 v14, v0, 1, 0
	s_waitcnt vmcnt(0) lgkmcnt(0)
	s_waitcnt lgkmcnt(0)
	s_barrier
; template <int TY> __device__ __forceinline__ void mc_item(const Params& p, ldsp lds, int item) {
;     ...
;         { f32x4 c0 = (f32x4){0.f, 0.f, 0.f, 0.f}, c1 = c0;
; #pragma unroll
;           for (int ks = 0; ks < DK / 32; ++ks) { const bf16x8 bq = ldfrag(QX, (16 * tt + l15) * PQ + 32 * ks + 8 * q4);
;               c0 = mma16(ldfrag(KTs, (16 * (2 * sp) + l15) * PQ + 32 * ks + 8 * q4), bq, c0);
;               c1 = mma16(ldfrag(KTs, (16 * (2 * sp + 1) + l15) * PQ + 32 * ks + 8 * q4), bq, c1); }
;           const int t = 16 * tt + l15;
;           const int tl = (j == jc) ? t : 4096;
; #pragma unroll
;           for (int jj = 0; jj < 4; ++jj) { if (32 * sp + 4 * q4 + jj > tl) c0[jj] = 0.f; if (32 * sp + 16 + 4 * q4 + jj > tl) c1[jj] = 0.f; }
;           u32x2 w; w.x = pk2(c0[0], c0[1]); w.y = pk2(c0[2], c0[3]); *(LAS u32x2*)(Pm + (size_t)(t * 72 + 32 * sp + 4 * q4) * 2) = w;
;           w.x = pk2(c1[0], c1[1]); w.y = pk2(c1[2], c1[3]); *(LAS u32x2*)(Pm + (size_t)(t * 72 + 32 * sp + 16 + 4 * q4) * 2) = w; }
;         if constexpr (TY == 2) __syncthreads(); else BSYNC();
; #pragma unroll
;         for (int ks = 0; ks < 2; ++ks) { bf16x8 pb[4];
; #pragma unroll
;             for (int tk = 0; tk < 4; ++tk) pb[tk] = ldfrag(Pm, (16 * tk + l15) * 72 + 32 * ks + 8 * q4);
; #pragma unroll
;             for (int ei = 0; ei < ET; ++ei) { const bf16x8 va = ldfrag(VTs, (16 * (wave * ET + ei) + l15) * 72 + 32 * ks + 8 * q4);
; #pragma unroll
;                 for (int tk = 0; tk < 4; ++tk) acc[ei][tk] = mma16(va, pb[tk], acc[ei][tk]); } }
;         if constexpr (TY == 2) __syncthreads(); else BSYNC(); }
;     if ((TY == 2 ? sc : c) != 0) { const bf16_t* STp = (TY == 2) ? (const bf16_t*)(p.ws + WS_ST) + ((size_t)bh * 8 + sc) * 512 * 256
;                                     : (const bf16_t*)(p.ws + WS_ST + (TY ? ST_HGRN : 0)) + ((size_t)bh * 32 + c) * 128 * DK;
;       ldsp QS = (TY == 2) ? QX : QH2;
;       bf16x8 sa[ET], sn[ET];
; #pragma unroll
;       for (int ei = 0; ei < ET; ++ei) sa[ei] = *(const bf16x8*)(STp + (size_t)(16 * (wave * ET + ei) + l15) * DK + 8 * q4);
; #pragma unroll 1
;       for (int ks = 0; ks < DK / 32; ++ks) { bf16x8 qb[4];
;           const int kn = (ks + 1 < DK / 32) ? ks + 1 : ks;
; #pragma unroll
;           for (int ei = 0; ei < ET; ++ei) sn[ei] = *(const bf16x8*)(STp + (size_t)(16 * (wave * ET + ei) + l15) * DK + 32 * kn + 8 * q4);
	ds_read_b128 v[0:3], v14 offset:34816
	v_and_or_b32 v15, s13, 48, v24
	v_mad_u32_u24 v4, v15, s20, v8
	v_lshl_add_u32 v16, v4, 1, 0
	ds_read_b128 v[4:7], v16
	ds_read_b128 v[10:13], v14 offset:39168
	ds_read_b128 v[18:21], v14 offset:34880
	s_waitcnt lgkmcnt(2)
	v_mfma_f32_16x16x32_bf16 v[0:3], v[0:3], v[4:7], 0
	v_lshlrev_b32_e32 v23, 2, v9
	v_or_b32_e32 v9, s1, v23
	v_cmp_gt_i32_e32 vcc, v9, v15
	s_waitcnt lgkmcnt(1)
	v_mfma_f32_16x16x32_bf16 v[4:7], v[10:13], v[4:7], 0
	ds_read_b128 v[10:13], v16 offset:64
	ds_read_b128 v[26:29], v14 offset:39232
	v_readlane_b32 s9, v255, 24
	s_movk_i32 s1, 0x90
	s_waitcnt lgkmcnt(1)
	v_mfma_f32_16x16x32_bf16 v[0:3], v[18:21], v[10:13], v[0:3]
	ds_read_b128 v[18:21], v14 offset:34944
	s_waitcnt lgkmcnt(1)
	v_mfma_f32_16x16x32_bf16 v[4:7], v[26:29], v[10:13], v[4:7]
	ds_read_b128 v[10:13], v16 offset:128
	s_waitcnt lgkmcnt(0)
	v_mfma_f32_16x16x32_bf16 v[0:3], v[18:21], v[10:13], v[0:3]
	ds_read_b128 v[18:21], v14 offset:39296
	ds_read_b128 v[26:29], v14 offset:35008
	s_waitcnt lgkmcnt(1)
	v_mfma_f32_16x16x32_bf16 v[4:7], v[18:21], v[10:13], v[4:7]
	ds_read_b128 v[10:13], v16 offset:192
	ds_read_b128 v[18:21], v14 offset:39360
	v_mad_u32_u24 v14, v15, s53, v9
	v_lshl_add_u32 v14, v14, 1, s9
	s_waitcnt lgkmcnt(1)
	v_mfma_f32_16x16x32_bf16 v[0:3], v[26:29], v[10:13], v[0:3]
	s_waitcnt lgkmcnt(0)
	v_mfma_f32_16x16x32_bf16 v[4:7], v[18:21], v[10:13], v[4:7]
	v_mov_b32_e32 v12, s41
	s_nop 4
	v_cndmask_b32_e32 v13, v0, v12, vcc
	v_or_b32_e32 v12, 16, v9
	v_cmp_gt_i32_e32 vcc, v12, v15
	v_mov_b32_e32 v12, s41
	v_or_b32_e32 v10, s13, v24
	v_cndmask_b32_e32 v4, v4, v12, vcc
	v_cmp_lt_i32_e32 vcc, v9, v15
	v_or_b32_e32 v12, 17, v9
	v_mul_lo_u32 v11, v10, s1
	v_cndmask_b32_e32 v0, v13, v0, vcc
	v_cndmask_b32_e32 v1, 0, v1, vcc
	v_cmp_le_i32_e32 vcc, v12, v15
	v_or_b32_e32 v12, 2, v9
	v_cvt_pk_bf16_f32 v0, v0, v1
	s_nop 0
	v_cndmask_b32_e32 v5, 0, v5, vcc
	v_cmp_le_i32_e32 vcc, v12, v15
	v_or_b32_e32 v12, 18, v9
	s_nop 0
	v_cndmask_b32_e32 v2, 0, v2, vcc
	v_cmp_le_i32_e32 vcc, v12, v15
	v_or_b32_e32 v12, 3, v9
	v_or_b32_e32 v9, 19, v9
	v_cndmask_b32_e32 v6, 0, v6, vcc
	v_cmp_le_i32_e32 vcc, v12, v15
	s_nop 1
	v_cndmask_b32_e32 v3, 0, v3, vcc
	v_cmp_le_i32_e32 vcc, v9, v15
	v_cvt_pk_bf16_f32 v1, v2, v3
	v_add3_u32 v9, 0, v25, v11
	ds_write_b64 v14, v[0:1]
	v_cndmask_b32_e32 v7, 0, v7, vcc
	v_cvt_pk_bf16_f32 v0, v4, v5
	v_cvt_pk_bf16_f32 v1, v6, v7
	ds_write_b64 v14, v[0:1] offset:32
	s_waitcnt vmcnt(0) lgkmcnt(0)
	s_waitcnt lgkmcnt(0)
	s_barrier
	ds_read_b128 v[0:3], v9 offset:52224
	v_mul_u32_u24_e32 v4, 0x90, v24
	v_add3_u32 v11, s9, v25, v4
	ds_read_b128 v[4:7], v11
	ds_read_b128 v[12:15], v11 offset:2304
	ds_read_b128 v[18:21], v11 offset:4608
	ds_read_b128 v[26:29], v11 offset:6912
	ds_read_b128 v[34:37], v9 offset:52288
	s_waitcnt lgkmcnt(2)
	v_mfma_f32_16x16x32_bf16 v[30:33], v[0:3], v[18:21], 0
	ds_read_b128 v[18:21], v11 offset:64
	s_and_b64 vcc, exec, s[10:11]
	v_mfma_f32_16x16x32_bf16 v[4:7], v[0:3], v[4:7], 0
	s_waitcnt lgkmcnt(0)
	v_mfma_f32_16x16x32_bf16 v[18:21], v[34:37], v[18:21], v[4:7]
	v_mfma_f32_16x16x32_bf16 v[12:15], v[0:3], v[12:15], 0
	s_nop 4
	ds_read_b128 v[4:7], v11 offset:2368
	v_mfma_f32_16x16x32_bf16 v[0:3], v[0:3], v[26:29], 0
	ds_read_b128 v[26:29], v11 offset:6976
	s_waitcnt lgkmcnt(1)
	v_mfma_f32_16x16x32_bf16 v[12:15], v[34:37], v[4:7], v[12:15]
	ds_read_b128 v[4:7], v11 offset:4672
	s_waitcnt vmcnt(0) lgkmcnt(0)
	s_waitcnt lgkmcnt(0)
	v_mfma_f32_16x16x32_bf16 v[4:7], v[34:37], v[4:7], v[30:33]
	s_barrier
	v_mfma_f32_16x16x32_bf16 v[0:3], v[34:37], v[26:29], v[0:3]
	s_cbranch_vccnz .LBB0_1246
	s_ashr_i32 s9, s8, 31
	s_lshl_b64 s[18:19], s[8:9], 20
	v_readlane_b32 s1, v254, 5
	s_add_u32 s18, s1, s18
	v_readlane_b32 s1, v254, 7
	v_ashrrev_i32_e32 v11, 31, v10
	s_addc_u32 s19, s1, s19
	v_lshlrev_b64 v[10:11], 8, v[10:11]
	v_lshl_add_u64 v[10:11], s[18:19], 0, v[10:11]
	v_lshlrev_b32_e32 v16, 1, v8
	v_lshl_add_u64 v[8:9], v[10:11], 0, v[16:17]
	v_mul_u32_u24_e32 v10, 0x110, v24
	s_add_i32 s1, 0, 0x4400
	v_add3_u32 v16, v10, v25, s1
	s_mov_b32 s1, 32
	v_mov_b64_e32 v[10:11], v[8:9]
	global_load_dwordx4 v[140:143], v[8:9], off
	global_load_dwordx4 v[144:147], v[8:9], off offset:64
	global_load_dwordx4 v[148:151], v[8:9], off offset:128
	global_load_dwordx4 v[152:155], v[8:9], off offset:192
	ds_read_b128 v[172:175], v16
	ds_read_b128 v[176:179], v16 offset:4352
	ds_read_b128 v[180:183], v16 offset:8704
	ds_read_b128 v[186:189], v16 offset:13056
.LBB0_1245:
	ds_read_b128 v[190:193], v16 offset:64
	ds_read_b128 v[194:197], v16 offset:4416
	ds_read_b128 v[218:221], v16 offset:8768
	ds_read_b128 v[222:225], v16 offset:13120
	s_waitcnt vmcnt(3) lgkmcnt(4)
	v_mfma_f32_16x16x32_bf16 v[18:21], v[140:143], v[172:175], v[18:21]
	v_mfma_f32_16x16x32_bf16 v[12:15], v[140:143], v[176:179], v[12:15]
	v_mfma_f32_16x16x32_bf16 v[4:7], v[140:143], v[180:183], v[4:7]
	v_mfma_f32_16x16x32_bf16 v[0:3], v[140:143], v[186:189], v[0:3]
	ds_read_b128 v[172:175], v16 offset:128
	ds_read_b128 v[176:179], v16 offset:4480
	ds_read_b128 v[180:183], v16 offset:8832
	ds_read_b128 v[186:189], v16 offset:13184
	s_waitcnt vmcnt(2) lgkmcnt(4)
	v_mfma_f32_16x16x32_bf16 v[18:21], v[144:147], v[190:193], v[18:21]
	v_mfma_f32_16x16x32_bf16 v[12:15], v[144:147], v[194:197], v[12:15]
	v_mfma_f32_16x16x32_bf16 v[4:7], v[144:147], v[218:221], v[4:7]
	v_mfma_f32_16x16x32_bf16 v[0:3], v[144:147], v[222:225], v[0:3]
	ds_read_b128 v[190:193], v16 offset:192
	ds_read_b128 v[194:197], v16 offset:4544
	ds_read_b128 v[218:221], v16 offset:8896
	ds_read_b128 v[222:225], v16 offset:13248
	s_waitcnt vmcnt(1) lgkmcnt(4)
	v_mfma_f32_16x16x32_bf16 v[18:21], v[148:151], v[172:175], v[18:21]
	v_mfma_f32_16x16x32_bf16 v[12:15], v[148:151], v[176:179], v[12:15]
	v_mfma_f32_16x16x32_bf16 v[4:7], v[148:151], v[180:183], v[4:7]
	v_mfma_f32_16x16x32_bf16 v[0:3], v[148:151], v[186:189], v[0:3]
	s_waitcnt vmcnt(0) lgkmcnt(0)
	v_mfma_f32_16x16x32_bf16 v[18:21], v[152:155], v[190:193], v[18:21]
	v_mfma_f32_16x16x32_bf16 v[12:15], v[152:155], v[194:197], v[12:15]
	v_mfma_f32_16x16x32_bf16 v[4:7], v[152:155], v[218:221], v[4:7]
	v_mfma_f32_16x16x32_bf16 v[0:3], v[152:155], v[222:225], v[0:3]
	v_add_u32_e32 v16, 0x100, v16
	s_movk_i32 s1, 0xa0
	s_movk_i32 s40, 0x60

; #define LAS __attribute__((address_space(3)))
; #define BSYNC() do { asm volatile("s_waitcnt vmcnt(0) lgkmcnt(0)" ::: "memory"); __syncthreads(); } while (0)
; template <int TY> __device__ __forceinline__ void mc_item(const Params& p, ldsp lds, int item) {
;     ...
;     const int bh = item >> 5, c = item & 31, b = bh >> 2, h = bh & 3, sc = c / NB, jc = c % NB, row0 = b * 2048 + c * 64;
;     ...
;     if (TY != 2) lds += LDSSHIFT;
;     ...
;     ldsp QX = lds, QH2 = lds + o_qh, KTs = lds + o_kt, VTs = lds + o_vt, Pm = lds + o_pm; LAS float* RED = (LAS float*)(lds + o_red);
;     const bf16_t* Pb = (const bf16_t*)(p.ws + WS_P);
;     constexpr int PP = TY == 2 ? NO : NE;
;     const int ecol = TY ? 256 + h * 128 : h * 64;
;     if (TY == 2) stage_rows<DK>(QX, PQ, Pb + (size_t)row0 * NO + O_Q + h * 256, NO, tid);
;     else { stage_rows<DK>(QX, PQ, (const bf16_t*)(p.ws + WS_QT) + (size_t)row0 * 768 + ecol, 768, tid);
;            stage_rows<DK>(QH2, PQ, (const bf16_t*)(p.ws + WS_QH) + (size_t)row0 * 768 + ecol, 768, tid); }
;     f32x4 acc[ET][4];
; #pragma unroll
;     for (int ei = 0; ei < ET; ++ei)
; #pragma unroll
;         for (int tk = 0; tk < 4; ++tk) acc[ei][tk] = (f32x4){0.f, 0.f, 0.f, 0.f};
;     const int voff = TY == 0 ? E_VA + h * 128 : (TY == 1 ? E_IB + h * 128 : O_V + h * 512);
;     const int tt = wave & 3, sp = wave >> 2;
;     u32x4 kr[TY == 2 ? 4 : 1], vr[TY == 2 ? 8 : 1];
;     if constexpr (TY == 2) { const size_t rowq = (size_t)b * 2048 + (sc * NB) * 64;
;         ld_rows<256>(kr, Pb + rowq * NO + O_K + h * 256, NO, tid); ld_T<512>(vr, Pb + rowq * NO + voff, NO, wave, lane); }
;     for (int j = 0; j <= jc; ++j) { const size_t rowj = (size_t)b * 2048 + (sc * NB + j) * 64;
;         if constexpr (TY == 2) { st_rows<256>(KTs, PQ, kr, tid); st_T<512>(VTs, 72, vr, wave, lane); }
;         else { stage_rows<DK>(KTs, PQ, (const bf16_t*)(p.ws + WS_KT) + rowj * 768 + ecol, 768, tid);
;                stage_T<DV>(VTs, 72, Pb + rowj * PP + voff, PP, wave, lane); }
;         if constexpr (TY == 2) { __syncthreads(); if (j < jc) { const size_t rown = rowj + 64; ld_rows<256>(kr, Pb + rown * NO + O_K + h * 256, NO, tid); ld_T<512>(vr, Pb + rown * NO + voff, NO, wave, lane); } }
;         else BSYNC();
.LBB0_1270:
	s_add_i32 s12, s8, 0xfffffc00
	s_and_b32 s1, s8, 31
	s_lshr_b32 s40, s12, 7
	s_lshl_b32 s9, s40, 11
	s_lshl_b32 s11, s1, 6
	s_or_b32 s9, s9, s11
	s_lshl_b32 s10, s12, 2
	v_mov_b32_e32 v22, v161
	s_and_b32 s10, s10, 0x180
	s_mul_i32 s16, s9, 0x600
	s_mul_hi_u32 s13, s9, 0x600
	s_add_u32 s14, s28, s16
	v_add_u32_e32 v6, 0x200, v22
	s_addc_u32 s15, s29, s13
	s_lshl_b32 s10, s10, 1
	v_ashrrev_i32_e32 v0, 31, v22
	v_ashrrev_i32_e32 v7, 31, v6
	s_add_u32 s14, s14, s10
	v_lshrrev_b32_e32 v0, 28, v0
	v_lshrrev_b32_e32 v7, 28, v7
	s_addc_u32 s15, s15, 0
	v_add_u32_e32 v0, v22, v0
	v_add_u32_e32 v7, v6, v7
	v_ashrrev_i32_e32 v40, 4, v0
	v_and_b32_e32 v0, 0x1ffffff0, v0
	v_mov_b64_e32 v[4:5], s[14:15]
	v_ashrrev_i32_e32 v41, 4, v7
	v_sub_u32_e32 v2, v22, v0
	v_mad_i64_i32 v[0:1], s[14:15], v40, s60, v[4:5]
	v_mad_i64_i32 v[4:5], s[14:15], v41, s60, v[4:5]
	s_add_u32 s14, s22, s16
	s_addc_u32 s13, s23, s13
	s_add_u32 s14, s14, s10
	s_addc_u32 s15, s13, 0
	v_mov_b64_e32 v[12:13], s[14:15]
	v_mad_i64_i32 v[8:9], s[14:15], v40, s60, v[12:13]
	v_mad_i64_i32 v[12:13], s[14:15], v41, s60, v[12:13]
	s_lshl_b64 s[14:15], s[40:41], 11
	s_or_b32 s11, s14, s11
	s_mul_hi_u32 s14, s11, 0x600
	s_mul_i32 s17, s15, 0x600
	v_readfirstlane_b32 s0, v22
	s_mul_i32 s16, s11, 0x600
	s_add_i32 s17, s14, s17
	s_mul_i32 s14, s11, 0x1e00
	s_mul_hi_u32 s11, s11, 0x1e00
	s_mulk_i32 s15, 0x1e00
	s_ashr_i32 s13, s0, 6
	s_add_i32 s11, s11, s15
	v_and_b32_e32 v7, 0x1ffffff0, v7
	s_add_u32 s14, s26, s14
	v_sub_u32_e32 v6, v6, v7
	s_addc_u32 s11, s27, s11
	v_lshlrev_b32_e32 v38, 3, v6
	s_add_u32 s14, s14, s10
	v_ashrrev_i32_e32 v39, 31, v38
	s_addc_u32 s15, s11, 0
	s_lshl_b32 s11, s13, 5
	v_and_b32_e32 v16, 31, v22
	v_lshlrev_b64 v[24:25], 1, v[38:39]
	v_and_or_b32 v39, s11, 32, v16
	v_mul_u32_u24_e32 v16, 0xf00, v39
	v_lshlrev_b32_e32 v16, 1, v16
	v_lshlrev_b32_e32 v36, 3, v2
	v_lshl_add_u64 v[20:21], s[14:15], 0, v[16:17]
	v_bfe_u32 v16, v22, 5, 1
	v_ashrrev_i32_e32 v37, 31, v36
	v_and_or_b32 v16, s13, -2, v16
	s_lshl_b32 s11, s13, 4
	s_ashr_i32 s13, s0, 3
	v_lshlrev_b64 v[18:19], 1, v[36:37]
	s_andn2_b32 s13, s13, 31
	v_lshl_add_u64 v[0:1], v[0:1], 0, v[18:19]
	s_add_u32 s14, s72, s16
	global_load_dwordx4 v[0:3], v[0:1], off offset:512
	s_addc_u32 s15, s73, s17
	v_lshlrev_b32_e32 v26, 3, v16
	s_add_u32 s14, s14, s10
	v_lshl_add_u64 v[4:5], v[4:5], 0, v[24:25]
	v_ashrrev_i32_e32 v27, 31, v26
	s_addc_u32 s15, s15, 0
	global_load_dwordx4 v[4:7], v[4:5], off offset:512
	v_lshl_add_u64 v[8:9], v[8:9], 0, v[18:19]
	v_lshl_add_u64 v[32:33], v[26:27], 1, v[20:21]
	v_mov_b64_e32 v[26:27], s[14:15]
	global_load_dwordx4 v[8:11], v[8:9], off offset:512
	v_lshl_add_u64 v[12:13], v[12:13], 0, v[24:25]
	v_mad_i64_i32 v[20:21], s[14:15], v40, s60, v[26:27]
	global_load_dwordx4 v[12:15], v[12:13], off offset:512
	v_lshl_add_u64 v[18:19], v[20:21], 0, v[18:19]
	v_mad_i64_i32 v[26:27], s[14:15], v41, s60, v[26:27]
	global_load_dwordx4 v[18:21], v[18:19], off offset:512
	v_lshl_add_u64 v[24:25], v[26:27], 0, v[24:25]
	v_add_co_u32_e32 v28, vcc, s57, v32
	global_load_dwordx4 v[24:27], v[24:25], off offset:512
	s_nop 0
	v_addc_co_u32_e32 v29, vcc, 0, v33, vcc
	global_load_dwordx4 v[28:31], v[28:29], off offset:1024
	s_mov_b64 s[14:15], 0x1400
	v_lshl_add_u64 v[32:33], v[32:33], 0, s[14:15]
	global_load_dwordx4 v[32:35], v[32:33], off offset:128
	s_movk_i32 s16, 0x88
	v_mad_u64_u32 v[36:37], s[14:15], v40, s16, v[36:37]
	v_lshl_add_u32 v36, v36, 1, 0
	v_and_b32_e32 v23, 15, v22
	s_cmp_eq_u32 s1, 0
	s_waitcnt vmcnt(0)
	ds_write_b128 v36, v[0:3]
	v_mad_u64_u32 v[0:1], s[14:15], v41, s16, v[38:39]
	s_movk_i32 s14, 0x240
	v_lshl_add_u32 v2, v0, 1, 0
	v_mul_lo_u32 v0, v16, s14
	ds_write_b128 v2, v[4:7]
	ds_write_b128 v36, v[8:11] offset:17408
	ds_write_b128 v2, v[12:15] offset:17408
	v_bfe_u32 v9, v22, 4, 2
	v_or_b32_e32 v0, v39, v0
	v_lshl_add_u32 v3, v0, 1, 0
	v_lshlrev_b32_e32 v8, 3, v9
	v_or_b32_e32 v0, s13, v23
	v_mad_u64_u32 v[0:1], s[14:15], v0, s16, v[8:9]
	ds_write_b128 v36, v[18:21] offset:34816
	ds_write_b128 v2, v[24:27] offset:34816
	ds_write_b16 v3, v28 offset:52224
	ds_write_b16_d16_hi v3, v28 offset:52368
	ds_write_b16 v3, v29 offset:52512
	ds_write_b16_d16_hi v3, v29 offset:52656
	ds_write_b16 v3, v30 offset:52800
	ds_write_b16_d16_hi v3, v30 offset:52944
	ds_write_b16 v3, v31 offset:53088
	ds_write_b16_d16_hi v3, v31 offset:53232
	ds_write_b16 v3, v32 offset:61440
	ds_write_b16_d16_hi v3, v32 offset:61584
	ds_write_b16 v3, v33 offset:61728
	ds_write_b16_d16_hi v3, v33 offset:61872
	ds_write_b16 v3, v34 offset:62016
	ds_write_b16_d16_hi v3, v34 offset:62160
	ds_write_b16 v3, v35 offset:62304
	ds_write_b16_d16_hi v3, v35 offset:62448
	v_lshl_add_u32 v14, v0, 1, 0
	s_waitcnt vmcnt(0) lgkmcnt(0)
	s_waitcnt lgkmcnt(0)
	s_barrier
; #define LAS __attribute__((address_space(3)))
; __device__ __forceinline__ unsigned pk2(float lo, float hi) { return pg8::cvt_pk_bf16(lo, hi); }
; __device__ __forceinline__ f32x4 mma16(bf16x8 a, bf16x8 b, f32x4 c) { return __builtin_amdgcn_mfma_f32_16x16x32_bf16(a, b, c, 0, 0, 0); }
; template <int TY> __device__ __forceinline__ void mc_item(const Params& p, ldsp lds, int item) {
;     ...
;         { f32x4 c0 = (f32x4){0.f, 0.f, 0.f, 0.f}, c1 = c0;
; #pragma unroll
;           for (int ks = 0; ks < DK / 32; ++ks) { const bf16x8 bq = ldfrag(QX, (16 * tt + l15) * PQ + 32 * ks + 8 * q4);
;               c0 = mma16(ldfrag(KTs, (16 * (2 * sp) + l15) * PQ + 32 * ks + 8 * q4), bq, c0);
;               c1 = mma16(ldfrag(KTs, (16 * (2 * sp + 1) + l15) * PQ + 32 * ks + 8 * q4), bq, c1); }
;           const int t = 16 * tt + l15;
;           const int tl = (j == jc) ? t : 4096;
; #pragma unroll
;           for (int jj = 0; jj < 4; ++jj) { if (32 * sp + 4 * q4 + jj > tl) c0[jj] = 0.f; if (32 * sp + 16 + 4 * q4 + jj > tl) c1[jj] = 0.f; }
;           u32x2 w; w.x = pk2(c0[0], c0[1]); w.y = pk2(c0[2], c0[3]); *(LAS u32x2*)(Pm + (size_t)(t * 72 + 32 * sp + 4 * q4) * 2) = w;
;           w.x = pk2(c1[0], c1[1]); w.y = pk2(c1[2], c1[3]); *(LAS u32x2*)(Pm + (size_t)(t * 72 + 32 * sp + 16 + 4 * q4) * 2) = w; }
;         if constexpr (TY == 2) __syncthreads(); else BSYNC();
; #pragma unroll
;         for (int ks = 0; ks < 2; ++ks) { bf16x8 pb[4];
; #pragma unroll
;             for (int tk = 0; tk < 4; ++tk) pb[tk] = ldfrag(Pm, (16 * tk + l15) * 72 + 32 * ks + 8 * q4);
; #pragma unroll
;             for (int ei = 0; ei < ET; ++ei) { const bf16x8 va = ldfrag(VTs, (16 * (wave * ET + ei) + l15) * 72 + 32 * ks + 8 * q4);
; #pragma unroll
;                 for (int tk = 0; tk < 4; ++tk) acc[ei][tk] = mma16(va, pb[tk], acc[ei][tk]); } }
;         if constexpr (TY == 2) __syncthreads(); else BSYNC(); }
;     if ((TY == 2 ? sc : c) != 0) { const bf16_t* STp = (TY == 2) ? (const bf16_t*)(p.ws + WS_ST) + ((size_t)bh * 8 + sc) * 512 * 256
;                                     : (const bf16_t*)(p.ws + WS_ST + (TY ? ST_HGRN : 0)) + ((size_t)bh * 32 + c) * 128 * DK;
;       ldsp QS = (TY == 2) ? QX : QH2;
;       bf16x8 sa[ET], sn[ET];
; #pragma unroll
;       for (int ei = 0; ei < ET; ++ei) sa[ei] = *(const bf16x8*)(STp + (size_t)(16 * (wave * ET + ei) + l15) * DK + 8 * q4);
	ds_read_b128 v[0:3], v14 offset:34816
	v_and_or_b32 v15, s11, 48, v23
	v_mad_u32_u24 v4, v15, s16, v8
	v_lshl_add_u32 v16, v4, 1, 0
	ds_read_b128 v[4:7], v16
	ds_read_b128 v[10:13], v14 offset:39168
	ds_read_b128 v[18:21], v14 offset:34880
	s_waitcnt lgkmcnt(2)
	v_mfma_f32_16x16x32_bf16 v[0:3], v[0:3], v[4:7], 0
	v_readlane_b32 s14, v255, 24
	s_waitcnt lgkmcnt(1)
	v_mfma_f32_16x16x32_bf16 v[4:7], v[10:13], v[4:7], 0
	ds_read_b128 v[10:13], v16 offset:64
	ds_read_b128 v[24:27], v14 offset:39232
	s_waitcnt lgkmcnt(1)
	v_mfma_f32_16x16x32_bf16 v[0:3], v[18:21], v[10:13], v[0:3]
	ds_read_b128 v[18:21], v14 offset:34944
	s_waitcnt lgkmcnt(1)
	v_mfma_f32_16x16x32_bf16 v[4:7], v[24:27], v[10:13], v[4:7]
	ds_read_b128 v[10:13], v16 offset:128
	v_lshlrev_b32_e32 v24, 2, v9
	v_or_b32_e32 v9, s13, v24
	s_waitcnt lgkmcnt(0)
	v_mfma_f32_16x16x32_bf16 v[0:3], v[18:21], v[10:13], v[0:3]
	ds_read_b128 v[18:21], v14 offset:39296
	ds_read_b128 v[26:29], v14 offset:35008
	v_cmp_gt_i32_e32 vcc, v9, v15
	s_movk_i32 s13, 0x90
	s_waitcnt lgkmcnt(1)
	v_mfma_f32_16x16x32_bf16 v[4:7], v[18:21], v[10:13], v[4:7]
	ds_read_b128 v[10:13], v16 offset:192
	ds_read_b128 v[18:21], v14 offset:39360
	v_mad_u32_u24 v14, v15, s53, v9
	v_lshl_add_u32 v14, v14, 1, s14
	s_waitcnt lgkmcnt(1)
	v_mfma_f32_16x16x32_bf16 v[0:3], v[26:29], v[10:13], v[0:3]
	v_and_b32_e32 v25, 48, v22
	s_waitcnt lgkmcnt(0)
	v_mfma_f32_16x16x32_bf16 v[4:7], v[18:21], v[10:13], v[4:7]
	v_mov_b32_e32 v12, s41
	s_nop 3
	v_cndmask_b32_e32 v13, v0, v12, vcc
	v_or_b32_e32 v12, 16, v9
	v_cmp_gt_i32_e32 vcc, v12, v15
	v_mov_b32_e32 v12, s41
	v_or_b32_e32 v10, s11, v23
	v_cndmask_b32_e32 v4, v4, v12, vcc
	v_cmp_lt_i32_e32 vcc, v9, v15
	v_or_b32_e32 v12, 17, v9
	v_mul_lo_u32 v11, v10, s13
	v_cndmask_b32_e32 v0, v13, v0, vcc
	v_cndmask_b32_e32 v1, 0, v1, vcc
	v_cmp_le_i32_e32 vcc, v12, v15
	v_or_b32_e32 v12, 2, v9
	v_cvt_pk_bf16_f32 v0, v0, v1
	s_nop 0
	v_cndmask_b32_e32 v5, 0, v5, vcc
	v_cmp_le_i32_e32 vcc, v12, v15
	v_or_b32_e32 v12, 18, v9
	s_nop 0
	v_cndmask_b32_e32 v2, 0, v2, vcc
	v_cmp_le_i32_e32 vcc, v12, v15
	v_or_b32_e32 v12, 3, v9
	v_or_b32_e32 v9, 19, v9
	v_cndmask_b32_e32 v6, 0, v6, vcc
	v_cmp_le_i32_e32 vcc, v12, v15
	s_nop 1
	v_cndmask_b32_e32 v3, 0, v3, vcc
	v_cmp_le_i32_e32 vcc, v9, v15
	v_cvt_pk_bf16_f32 v1, v2, v3
	v_add3_u32 v9, 0, v25, v11
	ds_write_b64 v14, v[0:1]
	v_cndmask_b32_e32 v7, 0, v7, vcc
	v_cvt_pk_bf16_f32 v0, v4, v5
	v_cvt_pk_bf16_f32 v1, v6, v7
	ds_write_b64 v14, v[0:1] offset:32
	s_waitcnt vmcnt(0) lgkmcnt(0)
	s_waitcnt lgkmcnt(0)
	s_barrier
	ds_read_b128 v[0:3], v9 offset:52224
	v_mul_u32_u24_e32 v4, 0x90, v23
	v_add3_u32 v11, s14, v25, v4
	ds_read_b128 v[4:7], v11
	ds_read_b128 v[12:15], v11 offset:2304
	ds_read_b128 v[18:21], v11 offset:4608
	ds_read_b128 v[26:29], v11 offset:6912
	ds_read_b128 v[34:37], v9 offset:52288
	s_waitcnt lgkmcnt(2)
	v_mfma_f32_16x16x32_bf16 v[30:33], v[0:3], v[18:21], 0
	ds_read_b128 v[18:21], v11 offset:64
	v_mfma_f32_16x16x32_bf16 v[4:7], v[0:3], v[4:7], 0
	s_waitcnt lgkmcnt(0)
	v_mfma_f32_16x16x32_bf16 v[18:21], v[34:37], v[18:21], v[4:7]
	v_mfma_f32_16x16x32_bf16 v[12:15], v[0:3], v[12:15], 0
	s_nop 4
	ds_read_b128 v[4:7], v11 offset:2368
	v_mfma_f32_16x16x32_bf16 v[0:3], v[0:3], v[26:29], 0
	ds_read_b128 v[26:29], v11 offset:6976
	s_waitcnt lgkmcnt(1)
	v_mfma_f32_16x16x32_bf16 v[12:15], v[34:37], v[4:7], v[12:15]
	ds_read_b128 v[4:7], v11 offset:4672
	s_waitcnt vmcnt(0) lgkmcnt(0)
	s_waitcnt lgkmcnt(0)
	v_mfma_f32_16x16x32_bf16 v[4:7], v[34:37], v[4:7], v[30:33]
	s_barrier
	v_mfma_f32_16x16x32_bf16 v[0:3], v[34:37], v[26:29], v[0:3]
	s_cbranch_scc1 .LBB0_1273
	s_lshr_b32 s40, s12, 5
	s_lshl_b64 s[12:13], s[40:41], 20
	v_readlane_b32 s14, v254, 4
	s_add_u32 s12, s14, s12
	v_readlane_b32 s14, v254, 6
	s_addc_u32 s13, s14, s13
	s_lshl_b32 s1, s1, 15
	s_add_u32 s12, s12, s1
	v_ashrrev_i32_e32 v11, 31, v10
	s_addc_u32 s13, s13, 0
	v_lshlrev_b64 v[10:11], 8, v[10:11]
	v_lshl_add_u64 v[10:11], s[12:13], 0, v[10:11]
	v_lshlrev_b32_e32 v16, 1, v8
	v_lshl_add_u64 v[8:9], v[10:11], 0, v[16:17]
	v_mul_u32_u24_e32 v10, 0x110, v23
	s_add_i32 s1, 0, 0x4400
	v_add3_u32 v16, v10, v25, s1
	s_mov_b32 s1, 32
	v_mov_b64_e32 v[10:11], v[8:9]
	global_load_dwordx4 v[140:143], v[8:9], off
	global_load_dwordx4 v[144:147], v[8:9], off offset:64
	global_load_dwordx4 v[148:151], v[8:9], off offset:128
	global_load_dwordx4 v[152:155], v[8:9], off offset:192
	ds_read_b128 v[172:175], v16
	ds_read_b128 v[176:179], v16 offset:4352
	ds_read_b128 v[180:183], v16 offset:8704
	ds_read_b128 v[186:189], v16 offset:13056
